# B3: one-hop release + acquire buffer_inv issued by every workgroup right behind its XSUB arrival atomic
# speedup vs baseline: 1.0203x; 1.0038x over previous
; __device__ __forceinline__ unsigned xb_ld(unsigned* p)              { return __hip_atomic_load(p, __ATOMIC_RELAXED, __HIP_MEMORY_SCOPE_AGENT); }
; __device__ __forceinline__ unsigned xb_add(unsigned* p, unsigned v) { return __hip_atomic_fetch_add(p, v, __ATOMIC_RELAXED, __HIP_MEMORY_SCOPE_AGENT); }
; #define XB_SPIN(cond, bar) do { unsigned _sp = 0; while (cond) { __builtin_amdgcn_s_sleep(1); \
;     if ((++_sp & 255u) == 0u) { if (xb_ld(&(bar)[XB_TMO])) break; if (_sp > XB_SPIN_CAP) { atomicAdd(&(bar)[XB_TMO], 1u); break; } } } } while (0)
; __device__ __forceinline__ void xcd_barrier(const XcdBarrier& b, int tid) {
;     ...
;         unsigned nloc = b.st[0], nx = b.st[1];
;         if (nloc == 0u) { xcd_barrier_complete(bar, b.x, nloc, nx); b.st[0] = nloc; b.st[1] = nx; }
;         const unsigned old = xb_add(&bar[XB_XSUB(b.x)], 1u);
;         const unsigned gen = old / nloc;
;         if (old + 1u == (gen + 1u) * nloc) {
;             __builtin_amdgcn_fence(__ATOMIC_RELEASE, "agent");
;             asm volatile("s_waitcnt vmcnt(0)" ::: "memory");
;             const unsigned og = xb_add(&bar[XB_TOP], 1u);
;             const unsigned tg = og / nx;
;             if (og + 1u == (tg + 1u) * nx) xb_add(&bar[XB_TOPGEN], 1u);
;             else XB_SPIN(xb_ld(&bar[XB_TOPGEN]) == tg, bar);
;             __builtin_amdgcn_fence(__ATOMIC_ACQUIRE, "agent");
;             xb_add(&bar[XB_XGEN(b.x)], 1u);
;             asm volatile("s_waitcnt vmcnt(0)" ::: "memory");
;         } else {
;             XB_SPIN(xb_ld(&bar[XB_XGEN(b.x)]) == gen, bar);
.LBB0_62:
	s_lshl_b32 s2, s26, 8
	s_add_u32 s2, s16, s2
	s_addc_u32 s3, s17, 0
	v_mov_b32_e32 v1, 0x1000
	v_mov_b32_e32 v3, 1
	global_atomic_add v3, v1, v3, s[2:3] offset:1024 sc0
	buffer_inv sc1
	v_cvt_f32_u32_e32 v1, v2
	v_sub_u32_e32 v4, 0, v2
	v_rcp_iflag_f32_e32 v1, v1
	s_nop 0
	v_mul_f32_e32 v1, 0x4f7ffffe, v1
	v_cvt_u32_f32_e32 v1, v1
	v_mul_lo_u32 v4, v4, v1
	v_mul_hi_u32 v4, v1, v4
	v_add_u32_e32 v1, v1, v4
	s_waitcnt vmcnt(1)
	v_mul_hi_u32 v1, v3, v1
	v_mul_lo_u32 v4, v1, v2
	v_sub_u32_e32 v4, v3, v4
	v_add_u32_e32 v5, 1, v1
	v_cmp_ge_u32_e32 vcc, v4, v2
	v_add_u32_e32 v3, 1, v3
	s_nop 0
	v_cndmask_b32_e32 v1, v1, v5, vcc
	v_sub_u32_e32 v5, v4, v2
	v_cndmask_b32_e32 v4, v4, v5, vcc
	v_add_u32_e32 v5, 1, v1
	v_cmp_ge_u32_e32 vcc, v4, v2
	s_nop 1
	v_cndmask_b32_e32 v1, v1, v5, vcc
	v_mul_lo_u32 v4, v2, v1
	v_add_u32_e32 v2, v4, v2
	v_cmp_ne_u32_e32 vcc, v3, v2
	s_and_saveexec_b64 s[4:5], vcc
	s_xor_b64 s[4:5], exec, s[4:5]
	s_cbranch_execz .LBB0_76
	s_waitcnt lgkmcnt(0)
	v_mov_b32_e32 v0, 0x2000
	global_load_dword v0, v0, s[2:3] offset:1024 sc1
	s_add_u32 s10, s2, 0x2400
	s_addc_u32 s11, s3, 0
	s_waitcnt vmcnt(0)
	v_cmp_eq_u32_e32 vcc, v0, v1
	s_and_saveexec_b64 s[6:7], vcc
	s_cbranch_execz .LBB0_75
	s_add_u32 s8, s82, 0x4200
	s_addc_u32 s9, s83, 0
	s_mov_b32 s24, 1
	s_mov_b64 s[12:13], 0
	v_mov_b32_e32 v0, 0
	s_branch .LBB0_66

; __device__ __forceinline__ unsigned xb_ld(unsigned* p)              { return __hip_atomic_load(p, __ATOMIC_RELAXED, __HIP_MEMORY_SCOPE_AGENT); }
; #define XB_SPIN(cond, bar) do { unsigned _sp = 0; while (cond) { __builtin_amdgcn_s_sleep(1); \
;     if ((++_sp & 255u) == 0u) { if (xb_ld(&(bar)[XB_TMO])) break; if (_sp > XB_SPIN_CAP) { atomicAdd(&(bar)[XB_TMO], 1u); break; } } } } while (0)
; __device__ __forceinline__ void xcd_barrier(const XcdBarrier& b, int tid) {
;     ...
;             XB_SPIN(xb_ld(&bar[XB_XGEN(b.x)]) == gen, bar);
;             __builtin_amdgcn_fence(__ATOMIC_ACQUIRE, "agent");
;             asm volatile("s_waitcnt vmcnt(0)" ::: "memory");
.LBB0_75:
	s_or_b64 exec, exec, s[6:7]
	s_waitcnt vmcnt(0)
	s_nop 0
	s_waitcnt vmcnt(0)

; __device__ __forceinline__ unsigned xb_add(unsigned* p, unsigned v) { return __hip_atomic_fetch_add(p, v, __ATOMIC_RELAXED, __HIP_MEMORY_SCOPE_AGENT); }
; __device__ __forceinline__ void xcd_barrier(const XcdBarrier& b, int tid) {
;     ...
;             __builtin_amdgcn_fence(__ATOMIC_ACQUIRE, "agent");
;             xb_add(&bar[XB_XGEN(b.x)], 1u);
;             asm volatile("s_waitcnt vmcnt(0)" ::: "memory");
.LBB0_93:
	s_or_b64 exec, exec, s[4:5]
	v_mov_b32_e32 v0, 0x2000
	v_mov_b32_e32 v1, 1
	s_waitcnt vmcnt(0)
	s_nop 0
	s_nop 0
	s_waitcnt vmcnt(0)

; __device__ __forceinline__ unsigned xb_ld(unsigned* p)              { return __hip_atomic_load(p, __ATOMIC_RELAXED, __HIP_MEMORY_SCOPE_AGENT); }
; __device__ __forceinline__ unsigned xb_add(unsigned* p, unsigned v) { return __hip_atomic_fetch_add(p, v, __ATOMIC_RELAXED, __HIP_MEMORY_SCOPE_AGENT); }
; #define XB_SPIN(cond, bar) do { unsigned _sp = 0; while (cond) { __builtin_amdgcn_s_sleep(1); \
;     if ((++_sp & 255u) == 0u) { if (xb_ld(&(bar)[XB_TMO])) break; if (_sp > XB_SPIN_CAP) { atomicAdd(&(bar)[XB_TMO], 1u); break; } } } } while (0)
; __device__ __forceinline__ void xcd_barrier(const XcdBarrier& b, int tid) {
;     ...
;         unsigned nloc = b.st[0], nx = b.st[1];
;         if (nloc == 0u) { xcd_barrier_complete(bar, b.x, nloc, nx); b.st[0] = nloc; b.st[1] = nx; }
;         const unsigned old = xb_add(&bar[XB_XSUB(b.x)], 1u);
;         const unsigned gen = old / nloc;
;         if (old + 1u == (gen + 1u) * nloc) {
;             __builtin_amdgcn_fence(__ATOMIC_RELEASE, "agent");
;             asm volatile("s_waitcnt vmcnt(0)" ::: "memory");
;             const unsigned og = xb_add(&bar[XB_TOP], 1u);
;             const unsigned tg = og / nx;
;             if (og + 1u == (tg + 1u) * nx) xb_add(&bar[XB_TOPGEN], 1u);
;             else XB_SPIN(xb_ld(&bar[XB_TOPGEN]) == tg, bar);
;             __builtin_amdgcn_fence(__ATOMIC_ACQUIRE, "agent");
;             xb_add(&bar[XB_XGEN(b.x)], 1u);
;             asm volatile("s_waitcnt vmcnt(0)" ::: "memory");
;         } else {
;             XB_SPIN(xb_ld(&bar[XB_XGEN(b.x)]) == gen, bar);
.LBB0_176:
	v_readlane_b32 s2, v254, 7
	v_readlane_b32 s3, v254, 8
	v_cvt_f32_u32_e32 v1, v2
	v_sub_u32_e32 v4, 0, v2
	v_rcp_iflag_f32_e32 v1, v1
	s_nop 1
	global_atomic_add v3, v161, v239, s[2:3] sc0
	buffer_inv sc1
	v_mul_f32_e32 v1, 0x4f7ffffe, v1
	v_cvt_u32_f32_e32 v1, v1
	v_mul_lo_u32 v4, v4, v1
	v_mul_hi_u32 v4, v1, v4
	v_add_u32_e32 v1, v1, v4
	s_waitcnt vmcnt(1)
	v_mul_hi_u32 v1, v3, v1
	v_mul_lo_u32 v4, v1, v2
	v_sub_u32_e32 v4, v3, v4
	v_add_u32_e32 v5, 1, v1
	v_cmp_ge_u32_e32 vcc, v4, v2
	v_add_u32_e32 v3, 1, v3
	s_nop 0
	v_cndmask_b32_e32 v1, v1, v5, vcc
	v_sub_u32_e32 v5, v4, v2
	v_cndmask_b32_e32 v4, v4, v5, vcc
	v_add_u32_e32 v5, 1, v1
	v_cmp_ge_u32_e32 vcc, v4, v2
	s_nop 1
	v_cndmask_b32_e32 v1, v1, v5, vcc
	v_mul_lo_u32 v4, v2, v1
	v_add_u32_e32 v2, v4, v2
	v_cmp_ne_u32_e32 vcc, v3, v2
	s_and_saveexec_b64 s[2:3], vcc
	s_xor_b64 s[2:3], exec, s[2:3]
	s_cbranch_execz .LBB0_190
	v_readlane_b32 s4, v254, 9
	v_readlane_b32 s5, v254, 10
	s_waitcnt lgkmcnt(0)
	s_nop 3
	global_load_dword v0, v161, s[4:5] sc1
	s_waitcnt vmcnt(0)
	v_cmp_eq_u32_e32 vcc, v0, v1
	s_and_saveexec_b64 s[4:5], vcc
	s_cbranch_execz .LBB0_189
	s_mov_b32 s18, 1
	s_mov_b64 s[6:7], 0
	s_branch .LBB0_180

; __device__ __forceinline__ unsigned xb_ld(unsigned* p)              { return __hip_atomic_load(p, __ATOMIC_RELAXED, __HIP_MEMORY_SCOPE_AGENT); }
; #define XB_SPIN(cond, bar) do { unsigned _sp = 0; while (cond) { __builtin_amdgcn_s_sleep(1); \
;     if ((++_sp & 255u) == 0u) { if (xb_ld(&(bar)[XB_TMO])) break; if (_sp > XB_SPIN_CAP) { atomicAdd(&(bar)[XB_TMO], 1u); break; } } } } while (0)
; __device__ __forceinline__ void xcd_barrier(const XcdBarrier& b, int tid) {
;     ...
;             XB_SPIN(xb_ld(&bar[XB_XGEN(b.x)]) == gen, bar);
;             __builtin_amdgcn_fence(__ATOMIC_ACQUIRE, "agent");
;             asm volatile("s_waitcnt vmcnt(0)" ::: "memory");
.LBB0_189:
	s_or_b64 exec, exec, s[4:5]
	s_waitcnt vmcnt(0)
	s_nop 0
	s_waitcnt vmcnt(0)

; __device__ __forceinline__ unsigned xb_add(unsigned* p, unsigned v) { return __hip_atomic_fetch_add(p, v, __ATOMIC_RELAXED, __HIP_MEMORY_SCOPE_AGENT); }
; __device__ __forceinline__ void xcd_barrier(const XcdBarrier& b, int tid) {
;     ...
;             __builtin_amdgcn_fence(__ATOMIC_ACQUIRE, "agent");
;             xb_add(&bar[XB_XGEN(b.x)], 1u);
;             asm volatile("s_waitcnt vmcnt(0)" ::: "memory");
.LBB0_207:
	s_or_b64 exec, exec, s[2:3]
	v_readlane_b32 s2, v254, 9
	v_readlane_b32 s3, v254, 10
	s_waitcnt vmcnt(0)
	s_nop 0
	s_nop 2
	s_nop 0
	s_waitcnt vmcnt(0)

; __device__ __forceinline__ unsigned xb_ld(unsigned* p)              { return __hip_atomic_load(p, __ATOMIC_RELAXED, __HIP_MEMORY_SCOPE_AGENT); }
; __device__ __forceinline__ unsigned xb_add(unsigned* p, unsigned v) { return __hip_atomic_fetch_add(p, v, __ATOMIC_RELAXED, __HIP_MEMORY_SCOPE_AGENT); }
; #define XB_SPIN(cond, bar) do { unsigned _sp = 0; while (cond) { __builtin_amdgcn_s_sleep(1); \
;     if ((++_sp & 255u) == 0u) { if (xb_ld(&(bar)[XB_TMO])) break; if (_sp > XB_SPIN_CAP) { atomicAdd(&(bar)[XB_TMO], 1u); break; } } } } while (0)
; __device__ __forceinline__ void xcd_barrier(const XcdBarrier& b, int tid) {
;     ...
;         unsigned nloc = b.st[0], nx = b.st[1];
;         if (nloc == 0u) { xcd_barrier_complete(bar, b.x, nloc, nx); b.st[0] = nloc; b.st[1] = nx; }
;         const unsigned old = xb_add(&bar[XB_XSUB(b.x)], 1u);
;         const unsigned gen = old / nloc;
;         if (old + 1u == (gen + 1u) * nloc) {
;             __builtin_amdgcn_fence(__ATOMIC_RELEASE, "agent");
;             asm volatile("s_waitcnt vmcnt(0)" ::: "memory");
;             const unsigned og = xb_add(&bar[XB_TOP], 1u);
;             const unsigned tg = og / nx;
;             if (og + 1u == (tg + 1u) * nx) xb_add(&bar[XB_TOPGEN], 1u);
;             else XB_SPIN(xb_ld(&bar[XB_TOPGEN]) == tg, bar);
;             __builtin_amdgcn_fence(__ATOMIC_ACQUIRE, "agent");
;             xb_add(&bar[XB_XGEN(b.x)], 1u);
;             asm volatile("s_waitcnt vmcnt(0)" ::: "memory");
;         } else {
;             XB_SPIN(xb_ld(&bar[XB_XGEN(b.x)]) == gen, bar);
.LBB0_1502:
	v_readlane_b32 s0, v254, 7
	v_readlane_b32 s1, v254, 8
	v_cvt_f32_u32_e32 v1, v2
	v_sub_u32_e32 v4, 0, v2
	v_rcp_iflag_f32_e32 v1, v1
	s_nop 1
	global_atomic_add v3, v161, v239, s[0:1] sc0
	buffer_inv sc1
	v_mul_f32_e32 v1, 0x4f7ffffe, v1
	v_cvt_u32_f32_e32 v1, v1
	v_mul_lo_u32 v4, v4, v1
	v_mul_hi_u32 v4, v1, v4
	v_add_u32_e32 v1, v1, v4
	s_waitcnt vmcnt(1)
	v_mul_hi_u32 v1, v3, v1
	v_mul_lo_u32 v4, v1, v2
	v_sub_u32_e32 v4, v3, v4
	v_add_u32_e32 v5, 1, v1
	v_cmp_ge_u32_e32 vcc, v4, v2
	v_add_u32_e32 v3, 1, v3
	s_nop 0
	v_cndmask_b32_e32 v1, v1, v5, vcc
	v_sub_u32_e32 v5, v4, v2
	v_cndmask_b32_e32 v4, v4, v5, vcc
	v_add_u32_e32 v5, 1, v1
	v_cmp_ge_u32_e32 vcc, v4, v2
	s_nop 1
	v_cndmask_b32_e32 v1, v1, v5, vcc
	v_mul_lo_u32 v4, v2, v1
	v_add_u32_e32 v2, v4, v2
	v_cmp_ne_u32_e32 vcc, v3, v2
	s_and_saveexec_b64 s[0:1], vcc
	s_xor_b64 s[4:5], exec, s[0:1]
	s_cbranch_execz .LBB0_1516
	v_readlane_b32 s0, v254, 9
	v_readlane_b32 s1, v254, 10
	s_waitcnt lgkmcnt(0)
	s_nop 3
	global_load_dword v0, v161, s[0:1] sc1
	s_waitcnt vmcnt(0)
	v_cmp_eq_u32_e32 vcc, v0, v1
	s_and_saveexec_b64 s[6:7], vcc
	s_cbranch_execz .LBB0_1515
	s_mov_b32 s0, 1
	s_mov_b64 s[8:9], 0
	s_branch .LBB0_1506

; __device__ __forceinline__ unsigned xb_add(unsigned* p, unsigned v) { return __hip_atomic_fetch_add(p, v, __ATOMIC_RELAXED, __HIP_MEMORY_SCOPE_AGENT); }
; __device__ __forceinline__ void xcd_barrier(const XcdBarrier& b, int tid) {
;     ...
;             __builtin_amdgcn_fence(__ATOMIC_ACQUIRE, "agent");
;             xb_add(&bar[XB_XGEN(b.x)], 1u);
;             asm volatile("s_waitcnt vmcnt(0)" ::: "memory");
.LBB0_1533:
	s_or_b64 exec, exec, s[4:5]
	v_readlane_b32 s0, v254, 9
	v_readlane_b32 s1, v254, 10
	s_waitcnt vmcnt(0)
	s_nop 0
	s_nop 2
	s_nop 0
	s_waitcnt vmcnt(0)

; __device__ __forceinline__ unsigned xb_ld(unsigned* p)              { return __hip_atomic_load(p, __ATOMIC_RELAXED, __HIP_MEMORY_SCOPE_AGENT); }
; __device__ __forceinline__ unsigned xb_add(unsigned* p, unsigned v) { return __hip_atomic_fetch_add(p, v, __ATOMIC_RELAXED, __HIP_MEMORY_SCOPE_AGENT); }
; #define XB_SPIN(cond, bar) do { unsigned _sp = 0; while (cond) { __builtin_amdgcn_s_sleep(1); \
;     if ((++_sp & 255u) == 0u) { if (xb_ld(&(bar)[XB_TMO])) break; if (_sp > XB_SPIN_CAP) { atomicAdd(&(bar)[XB_TMO], 1u); break; } } } } while (0)
; __device__ __forceinline__ void xcd_barrier(const XcdBarrier& b, int tid) {
;     ...
;         unsigned nloc = b.st[0], nx = b.st[1];
;         if (nloc == 0u) { xcd_barrier_complete(bar, b.x, nloc, nx); b.st[0] = nloc; b.st[1] = nx; }
;         const unsigned old = xb_add(&bar[XB_XSUB(b.x)], 1u);
;         const unsigned gen = old / nloc;
;         if (old + 1u == (gen + 1u) * nloc) {
;             __builtin_amdgcn_fence(__ATOMIC_RELEASE, "agent");
;             asm volatile("s_waitcnt vmcnt(0)" ::: "memory");
;             const unsigned og = xb_add(&bar[XB_TOP], 1u);
;             const unsigned tg = og / nx;
;             if (og + 1u == (tg + 1u) * nx) xb_add(&bar[XB_TOPGEN], 1u);
;             else XB_SPIN(xb_ld(&bar[XB_TOPGEN]) == tg, bar);
;             __builtin_amdgcn_fence(__ATOMIC_ACQUIRE, "agent");
;             xb_add(&bar[XB_XGEN(b.x)], 1u);
;             asm volatile("s_waitcnt vmcnt(0)" ::: "memory");
;         } else {
;             XB_SPIN(xb_ld(&bar[XB_XGEN(b.x)]) == gen, bar);
.LBB0_1826:
	v_readlane_b32 s2, v254, 7
	v_mov_b32_e32 v3, 0
	v_mov_b32_e32 v1, 1
	v_readlane_b32 s3, v254, 8
	v_sub_u32_e32 v5, 0, v2
	s_nop 3
	global_atomic_add v4, v3, v1, s[2:3] sc0
	buffer_inv sc1
	v_cvt_f32_u32_e32 v1, v2
	v_rcp_iflag_f32_e32 v1, v1
	s_nop 0
	v_mul_f32_e32 v1, 0x4f7ffffe, v1
	v_cvt_u32_f32_e32 v1, v1
	v_mul_lo_u32 v5, v5, v1
	v_mul_hi_u32 v5, v1, v5
	v_add_u32_e32 v1, v1, v5
	s_waitcnt vmcnt(1)
	v_mul_hi_u32 v1, v4, v1
	v_mul_lo_u32 v5, v1, v2
	v_sub_u32_e32 v5, v4, v5
	v_add_u32_e32 v6, 1, v1
	v_cmp_ge_u32_e32 vcc, v5, v2
	v_add_u32_e32 v4, 1, v4
	s_nop 0
	v_cndmask_b32_e32 v1, v1, v6, vcc
	v_sub_u32_e32 v6, v5, v2
	v_cndmask_b32_e32 v5, v5, v6, vcc
	v_add_u32_e32 v6, 1, v1
	v_cmp_ge_u32_e32 vcc, v5, v2
	s_nop 1
	v_cndmask_b32_e32 v1, v1, v6, vcc
	v_mul_lo_u32 v5, v2, v1
	v_add_u32_e32 v2, v5, v2
	v_cmp_ne_u32_e32 vcc, v4, v2
	s_and_saveexec_b64 s[2:3], vcc
	s_xor_b64 s[2:3], exec, s[2:3]
	s_cbranch_execz .LBB0_1840
	v_readlane_b32 s4, v254, 9
	v_readlane_b32 s5, v254, 10
	s_waitcnt lgkmcnt(0)
	s_nop 3
	global_load_dword v0, v3, s[4:5] sc1
	s_waitcnt vmcnt(0)
	v_cmp_eq_u32_e32 vcc, v0, v1
	s_and_saveexec_b64 s[4:5], vcc
	s_cbranch_execz .LBB0_1839
	s_mov_b32 s16, 1
	s_mov_b64 s[6:7], 0
	v_mov_b32_e32 v0, 0
	s_branch .LBB0_1830

; __device__ __forceinline__ unsigned xb_add(unsigned* p, unsigned v) { return __hip_atomic_fetch_add(p, v, __ATOMIC_RELAXED, __HIP_MEMORY_SCOPE_AGENT); }
; __device__ __forceinline__ void xcd_barrier(const XcdBarrier& b, int tid) {
;     ...
;             __builtin_amdgcn_fence(__ATOMIC_ACQUIRE, "agent");
;             xb_add(&bar[XB_XGEN(b.x)], 1u);
;             asm volatile("s_waitcnt vmcnt(0)" ::: "memory");
.LBB0_1857:
	s_or_b64 exec, exec, s[2:3]
	v_readlane_b32 s2, v254, 9
	v_mov_b32_e32 v0, 0
	v_mov_b32_e32 v1, 1
	v_readlane_b32 s3, v254, 10
	s_waitcnt vmcnt(0)
	s_nop 0
	s_nop 2
	s_nop 0
	s_waitcnt vmcnt(0)
